# plus NSA window tiles: branch-free mode-0 fast path for score bias/mask block
# baseline (speedup 1.0000x reference)
.LBB0_740:
	v_mov_b32_e32 v1, s74
	ds_read_b32 v1, v1
	s_and_b32 s68, s69, 1
	s_mul_i32 s69, s68, 0x2400
	s_add_i32 s91, s69, 0
	s_lshl_b32 s68, s68, 9
	s_waitcnt lgkmcnt(0)
	v_readfirstlane_b32 s69, v1
	s_and_b32 s90, s69, 0xff
	v_lshl_add_u32 v2, s90, 6, v155
	v_cvt_f32_i32_e32 v2, v2
	v_and_b32_e32 v1, 0x100, v1
	v_cmp_eq_u32_e32 vcc, 0, v1
	s_sub_i32 s88, s91, s68
	v_mul_f32_e32 v1, v149, v2
	s_and_b64 vcc, exec, vcc
	s_mov_b64 s[68:69], -1
	s_cbranch_vccnz .LBB0_844
	v_add3_u32 v14, s91, v148, v107
	v_add3_u32 v15, s91, v157, v107
	ds_read_b128 v[2:5], v14
	ds_read_b128 v[6:9], v14 offset:32
	ds_read_b128 v[10:13], v14 offset:64
	ds_read_b128 v[166:169], v14 offset:96
	ds_read_b128 v[170:173], v15
	ds_read_b128 v[174:177], v15 offset:32
	ds_read_b128 v[178:181], v15 offset:64
	s_cmp_eq_u32 s90, s75
	s_cselect_b32 s68, 2, 0
	s_cmp_lg_u32 s90, s78
	s_cselect_b32 s76, s68, 1
	s_cmp_gt_i32 s76, 1
	s_mov_b64 s[68:69], -1
	s_waitcnt lgkmcnt(6)
	v_mfma_f32_32x32x16_bf16 v[48:63], v[2:5], v[88:91], 0
	ds_read_b128 v[2:5], v15 offset:96
	s_waitcnt lgkmcnt(6)
	v_mfma_f32_32x32x16_bf16 v[48:63], v[6:9], v[80:83], v[48:63]
	s_waitcnt lgkmcnt(5)
	v_mfma_f32_32x32x16_bf16 v[48:63], v[10:13], v[84:87], v[48:63]
	s_waitcnt lgkmcnt(4)
	v_mfma_f32_32x32x16_bf16 v[48:63], v[166:169], v[92:95], v[48:63]
	s_waitcnt lgkmcnt(3)
	v_mfma_f32_32x32x16_bf16 v[64:79], v[170:173], v[88:91], 0
	s_waitcnt lgkmcnt(2)
	v_mfma_f32_32x32x16_bf16 v[64:79], v[174:177], v[80:83], v[64:79]
	s_waitcnt lgkmcnt(1)
	v_mfma_f32_32x32x16_bf16 v[64:79], v[178:181], v[84:87], v[64:79]
	s_waitcnt lgkmcnt(0)
	v_mfma_f32_32x32x16_bf16 v[64:79], v[2:5], v[92:95], v[64:79]
	v_add_f32_e32 v2, 0, v1
	v_fmamk_f32 v5, v149, 0x42000000, v1
	v_fmac_f32_e32 v2, 0x3e38aa3b, v48
	s_nop 8
	v_fmac_f32_e32 v5, 0x3e38aa3b, v64
	s_cmp_eq_u32 s76, 0
	s_cbranch_scc1 .Lnsa_m0
	s_cmp_gt_i32 s76, 1
	s_cbranch_scc0 .LBB0_743
	v_readlane_b32 s4, v254, 15
	v_readlane_b32 s5, v254, 16
	v_cndmask_b32_e64 v3, v194, v5, s[86:87]
	s_mov_b64 s[68:69], 0
	v_cndmask_b32_e64 v4, v194, v2, s[4:5]

.LBB0_836:
	v_mov_b32_e32 v199, v2
	v_mov_b32_e32 v197, v48
	s_branch .LBB0_837
.Lnsa_m0:
	v_mov_b32_e32 v4, v2
	v_mov_b32_e32 v3, v5
	v_add_f32_e32 v6, v149, v1
	v_fmamk_f32 v5, v149, 0x42040000, v1
	v_fmac_f32_e32 v6, 0x3e38aa3b, v49
	v_fmac_f32_e32 v5, 0x3e38aa3b, v65
	v_fma_f32 v8, 2.0, v149, v1
	v_fmamk_f32 v7, v149, 0x42080000, v1
	v_fmac_f32_e32 v8, 0x3e38aa3b, v50
	v_fmac_f32_e32 v7, 0x3e38aa3b, v66
	v_fmamk_f32 v9, v149, 0x40400000, v1
	v_fmamk_f32 v10, v149, 0x420c0000, v1
	v_fmac_f32_e32 v9, 0x3e38aa3b, v51
	v_fmac_f32_e32 v10, 0x3e38aa3b, v67
	v_fmamk_f32 v12, v149, 0x41000000, v1
	v_fmamk_f32 v11, v149, 0x42200000, v1
	v_fmac_f32_e32 v12, 0x3e38aa3b, v52
	v_fmac_f32_e32 v11, 0x3e38aa3b, v68
	v_fmamk_f32 v14, v149, 0x41100000, v1
	v_fmamk_f32 v13, v149, 0x42240000, v1
	v_fmac_f32_e32 v14, 0x3e38aa3b, v53
	v_fmac_f32_e32 v13, 0x3e38aa3b, v69
	v_fmamk_f32 v166, v149, 0x41200000, v1
	v_fmamk_f32 v15, v149, 0x42280000, v1
	v_fmac_f32_e32 v166, 0x3e38aa3b, v54
	v_fmac_f32_e32 v15, 0x3e38aa3b, v70
	v_fmamk_f32 v168, v149, 0x41300000, v1
	v_fmamk_f32 v167, v149, 0x422c0000, v1
	v_fmac_f32_e32 v168, 0x3e38aa3b, v55
	v_fmac_f32_e32 v167, 0x3e38aa3b, v71
	v_fmamk_f32 v170, v149, 0x41800000, v1
	v_fmamk_f32 v169, v149, 0x42400000, v1
	v_fmac_f32_e32 v170, 0x3e38aa3b, v56
	v_fmac_f32_e32 v169, 0x3e38aa3b, v72
	v_fmamk_f32 v172, v149, 0x41880000, v1
	v_fmamk_f32 v171, v149, 0x42440000, v1
	v_fmac_f32_e32 v172, 0x3e38aa3b, v57
	v_fmac_f32_e32 v171, 0x3e38aa3b, v73
	v_fmamk_f32 v175, v149, 0x41900000, v1
	v_fmamk_f32 v174, v149, 0x42480000, v1
	v_fmac_f32_e32 v175, 0x3e38aa3b, v58
	v_fmac_f32_e32 v174, 0x3e38aa3b, v74
	v_fmamk_f32 v179, v149, 0x41980000, v1
	v_fmamk_f32 v176, v149, 0x424c0000, v1
	v_fmac_f32_e32 v179, 0x3e38aa3b, v59
	v_fmac_f32_e32 v176, 0x3e38aa3b, v75
	v_fmamk_f32 v178, v149, 0x41c00000, v1
	v_fmamk_f32 v173, v149, 0x42600000, v1
	v_fmac_f32_e32 v178, 0x3e38aa3b, v60
	v_fmac_f32_e32 v173, 0x3e38aa3b, v76
	v_fmamk_f32 v181, v149, 0x41c80000, v1
	v_fmamk_f32 v177, v149, 0x42640000, v1
	v_fmac_f32_e32 v181, 0x3e38aa3b, v61
	v_fmac_f32_e32 v177, 0x3e38aa3b, v77
	v_fmamk_f32 v198, v149, 0x41d00000, v1
	v_fmamk_f32 v180, v149, 0x42680000, v1
	v_fmac_f32_e32 v198, 0x3e38aa3b, v62
	v_fmac_f32_e32 v180, 0x3e38aa3b, v78
	v_fmamk_f32 v199, v149, 0x41d80000, v1
	v_fmamk_f32 v197, v149, 0x426c0000, v1
	v_fmac_f32_e32 v199, 0x3e38aa3b, v63
	v_fmac_f32_e32 v197, 0x3e38aa3b, v79
